# NSA far-tile loop: register prefetch of the next tile issued after the tile scan
# baseline (speedup 1.0000x reference)
;   DI int next(int t) const { for (int j = t + 1; j < 128; ++j) if (inu(j) && !farj(j)) return j; return -1; }
;   DI int next(int t) const { for (int j = t + 1; j < 128; ++j) if (inu(j) && farj(j)) return j; return -1; }
; template <int DK, bool PV, bool PF, class Ctx>
; DI void attn_run(const bf16x8 (&qf)[DK / 16], f32x16 (&o)[4], float& m, float& l, const bf16* K1, int ldk1,
;                  const bf16* K2, int ldk2, const bf16* Vt, int ldv, int first, Ctx& ctx, char* smem) {
;     ...
;   auto sstore = [&]() {
;     stk(0, rk0); stk(1, rk1); stk(2, rk2); stk(3, rk3);
;     if (NKC > 4) { stk(4, rk4); stk(5, rk5); }
; #pragma unroll
;     for (int i = 0; i < 4; ++i) {
;       int c = tid + 256 * i;
;       int d = c >> 3, cc = c & 7;
;       uint2* dst = (uint2*)(Vs + d * 68 + cc * 8);
;       dst[0] = make_uint2(rv[i].x, rv[i].y);
;       dst[1] = make_uint2(rv[i].z, rv[i].w);
;     }
;     if (tid < 64) ((float*)(smem + AT_AUX))[tid] = raux;
;   };
;   if (PF) gload(tcur * 64);
;   while (tcur >= 0) {
;     __syncthreads();
;     if (!PF) gload(tcur * 64);
;     sstore();
;     __syncthreads();
;     int tnext = ctx.next(tcur);
;     if (PF && tnext >= 0) gload(tnext * 64);
.LBB0_760:
	s_cmp_lt_i32 s26, 0
	s_mov_b32 s6, 0
	s_cbranch_scc1 .LBB0_776
	v_add_u32_e32 v7, s6, v189
	v_ashrrev_i32_e32 v0, 31, v7
	v_lshrrev_b32_e32 v0, 28, v0
	v_add_u32_e32 v0, v7, v0
	v_lshrrev_b32_e32 v2, 4, v0
	v_and_b32_e32 v0, 0xffffff0, v0
	v_sub_u32_e32 v0, v7, v0
	v_add_u32_e32 v4, 0x100, v7
	v_lshlrev_b32_e32 v9, 4, v0
	v_ashrrev_i32_e32 v0, 31, v4
	v_lshrrev_b32_e32 v0, 28, v0
	v_add_u32_e32 v0, v4, v0
	v_mul_lo_u32 v8, v2, s73
	v_lshrrev_b32_e32 v2, 4, v0
	v_and_b32_e32 v0, 0xffffff0, v0
	v_sub_u32_e32 v0, v4, v0
	v_add_u32_e32 v12, 0x200, v7
	v_lshlrev_b32_e32 v11, 4, v0
	v_ashrrev_i32_e32 v0, 31, v12
	v_lshrrev_b32_e32 v0, 28, v0
	v_add_u32_e32 v0, v12, v0
	v_mul_lo_u32 v10, v2, s73
	v_lshrrev_b32_e32 v2, 4, v0
	v_and_b32_e32 v0, 0xffffff0, v0
	v_sub_u32_e32 v0, v12, v0
	v_add_u32_e32 v80, 0x300, v7
	v_lshlrev_b32_e32 v82, 4, v0
	v_ashrrev_i32_e32 v0, 31, v80
	v_lshrrev_b32_e32 v0, 28, v0
	v_add_u32_e32 v0, v80, v0
	v_mul_lo_u32 v13, v2, s73
	v_lshrrev_b32_e32 v2, 4, v0
	v_and_b32_e32 v0, 0xffffff0, v0
	v_sub_u32_e32 v0, v80, v0
	v_lshlrev_b32_e32 v84, 4, v0
	v_lshlrev_b32_e32 v0, 4, v7
	v_mul_lo_u32 v83, v2, s73
	v_lshrrev_b32_e32 v2, 3, v7
	v_and_b32_e32 v0, 0x70, v0
	v_mad_u64_u32 v[2:3], s[6:7], v2, s68, v[0:1]
	v_lshrrev_b32_e32 v3, 3, v4
	v_mad_u64_u32 v[4:5], s[6:7], v3, s68, v[0:1]
	v_lshrrev_b32_e32 v3, 3, v12
	v_mad_u64_u32 v[14:15], s[6:7], v3, s68, v[0:1]
	v_lshrrev_b32_e32 v3, 3, v80
	v_mad_u64_u32 v[80:81], s[6:7], v3, s68, v[0:1]
	v_cmp_gt_i32_e64 s[10:11], 64, v7
	v_lshlrev_b32_e32 v7, 2, v7
	v_add_u32_e32 v8, v8, v9
	v_add_u32_e32 v9, v10, v11
	v_add_u32_e32 v10, v13, v82
	v_add_u32_e32 v11, v83, v84
	v_add_u32_e32 v12, 0x6400, v2
	v_add_u32_e32 v13, 0x6400, v4
	v_add_u32_e32 v14, 0x6400, v14
	v_add_u32_e32 v15, 0x6400, v80
	s_branch .Lfar_first
.LBB0_762:
	s_waitcnt lgkmcnt(0)
	s_barrier
	s_waitcnt vmcnt(7)
	ds_write_b128 v8, v[196:199]
	s_waitcnt vmcnt(6)
	ds_write_b128 v9, v[200:203]
	s_waitcnt vmcnt(5)
	ds_write_b128 v10, v[204:207]
	s_waitcnt vmcnt(4)
	ds_write_b128 v11, v[220:223]
	s_waitcnt vmcnt(3)
	ds_write2_b64 v12, v[240:241], v[242:243] offset1:1
	s_waitcnt vmcnt(2)
	ds_write2_b64 v13, v[244:245], v[246:247] offset1:1
	s_waitcnt vmcnt(1)
	ds_write2_b64 v14, v[248:249], v[250:251] offset1:1
	s_waitcnt vmcnt(0)
	ds_write2_b64 v15, v[182:183], v[184:185] offset1:1
	s_branch .Lfar_stored

;   DI int next(int t) const { for (int j = t + 1; j < 128; ++j) if (inu(j) && !farj(j)) return j; return -1; }
;   DI int next(int t) const { for (int j = t + 1; j < 128; ++j) if (inu(j) && farj(j)) return j; return -1; }
; template <int DK, bool PV, bool PF, class Ctx>
; DI void attn_run(const bf16x8 (&qf)[DK / 16], f32x16 (&o)[4], float& m, float& l, const bf16* K1, int ldk1,
;                  const bf16* K2, int ldk2, const bf16* Vt, int ldv, int first, Ctx& ctx, char* smem) {
;     ...
;     if (tid < 64) ((float*)(smem + AT_AUX))[tid] = raux;
;   };
;   if (PF) gload(tcur * 64);
;   while (tcur >= 0) {
;     __syncthreads();
;     if (!PF) gload(tcur * 64);
;     sstore();
;     __syncthreads();
;     int tnext = ctx.next(tcur);
.Lfar_stored:
	s_and_saveexec_b64 s[6:7], s[10:11]
	ds_write_b32 v7, v1 offset:43008
	s_or_b64 exec, exec, s[6:7]
	s_cmpk_gt_u32 s26, 0x7e
	s_mov_b32 s6, -1
	s_waitcnt lgkmcnt(0)
	s_barrier
	s_cbranch_scc1 .LBB0_772
	s_add_i32 s27, s64, 0x7f
	s_mov_b32 s36, s26
	s_branch .LBB0_767

; DI int otid() { int z; asm volatile("s_mov_b32 %0, 0" : "=s"(z)); return (int)threadIdx.x + z; }
;   DI float aux(int key) const { return (cuml[key] + cpre[key >> 7]) * LOG2E; }
;           DI float aux(int key) const { int n = key < 511 ? key : 510; return __int_as_float(pos[16 * n + 31]); }
;   DI int next(int t) const { for (int j = t + 1; j < 128; ++j) if (inu(j) && !farj(j)) return j; return -1; }
;   DI float aux(int key) const { return __int_as_float(pos[key]); }
;   DI int next(int t) const { for (int j = t + 1; j < 128; ++j) if (inu(j) && farj(j)) return j; return -1; }
;   DI float aux(int key) const { return __int_as_float(pos[key]); }
; template <int DK, bool PV, bool PF, class Ctx>
; DI void attn_run(const bf16x8 (&qf)[DK / 16], f32x16 (&o)[4], float& m, float& l, const bf16* K1, int ldk1,
;                  const bf16* K2, int ldk2, const bf16* Vt, int ldv, int first, Ctx& ctx, char* smem) {
;     ...
;   auto gload = [&](int key0) {
;     rk0 = ldk(0, key0); rk1 = ldk(1, key0); rk2 = ldk(2, key0); rk3 = ldk(3, key0);
;     if (NKC > 4) { rk4 = ldk(4, key0); rk5 = ldk(5, key0); }
;     const int tl = otid();
; #pragma unroll
;     for (int i = 0; i < 4; ++i) {
;       int c = tl + 256 * i;
;       int d = c >> 3, cc = c & 7;
;       rv[i] = *(const uint4*)(Vt + (size_t)d * ldv + key0 + cc * 8);
;     }
;     raux = (tid < 64) ? ctx.aux(key0 + tid) : 0.f;
;   };
;     ...
;     int tnext = ctx.next(tcur);
;     if (PF && tnext >= 0) gload(tnext * 64);
.LBB0_772:
	s_cmp_lt_i32 s6, 0
	s_cbranch_scc1 .Lfar_nopf
	s_mov_b32 s12, 0
	s_lshl_b32 s64, s6, 6
	v_add_u32_e32 v0, s12, v189
	v_ashrrev_i32_e32 v2, 31, v0
	v_lshrrev_b32_e32 v2, 28, v2
	v_add_u32_e32 v2, v0, v2
	v_ashrrev_i32_e32 v3, 4, v2
	v_and_b32_e32 v2, 0x1ffffff0, v2
	v_sub_u32_e32 v0, v0, v2
	v_add_u32_e32 v2, s64, v3
	v_mov_b64_e32 v[88:89], s[42:43]
	v_lshlrev_b32_e32 v4, 3, v0
	v_mad_i64_i32 v[2:3], s[12:13], v2, s67, v[88:89]
	v_ashrrev_i32_e32 v5, 31, v4
	v_lshl_add_u64 v[2:3], v[4:5], 1, v[2:3]
	global_load_dwordx4 v[196:199], v[2:3], off
	s_mov_b32 s12, 0
	s_nop 0
	v_add_u32_e32 v0, s12, v208
	v_ashrrev_i32_e32 v80, 31, v0
	v_lshrrev_b32_e32 v80, 28, v80
	v_add_u32_e32 v80, v0, v80
	v_ashrrev_i32_e32 v81, 4, v80
	v_and_b32_e32 v80, 0x1ffffff0, v80
	v_sub_u32_e32 v0, v0, v80
	v_add_u32_e32 v80, s64, v81
	v_lshlrev_b32_e32 v82, 3, v0
	v_mad_i64_i32 v[80:81], s[12:13], v80, s67, v[88:89]
	v_ashrrev_i32_e32 v83, 31, v82
	v_lshl_add_u64 v[80:81], v[82:83], 1, v[80:81]
	global_load_dwordx4 v[200:203], v[80:81], off
	s_mov_b32 s12, 0
	s_nop 0
	v_add_u32_e32 v0, s12, v209
	v_ashrrev_i32_e32 v84, 31, v0
	v_lshrrev_b32_e32 v84, 28, v84
	v_add_u32_e32 v84, v0, v84
	v_ashrrev_i32_e32 v85, 4, v84
	v_and_b32_e32 v84, 0x1ffffff0, v84
	v_sub_u32_e32 v0, v0, v84
	v_add_u32_e32 v84, s64, v85
	v_lshlrev_b32_e32 v86, 3, v0
	v_mad_i64_i32 v[84:85], s[12:13], v84, s67, v[88:89]
	v_ashrrev_i32_e32 v87, 31, v86
	v_lshl_add_u64 v[84:85], v[86:87], 1, v[84:85]
	global_load_dwordx4 v[204:207], v[84:85], off
	s_mov_b32 s12, 0
	s_nop 0
	v_add_u32_e32 v0, s12, v210
	v_ashrrev_i32_e32 v90, 31, v0
	v_lshrrev_b32_e32 v90, 28, v90
	v_add_u32_e32 v90, v0, v90
	v_ashrrev_i32_e32 v91, 4, v90
	v_and_b32_e32 v90, 0x1ffffff0, v90
	v_sub_u32_e32 v0, v0, v90
	v_add_u32_e32 v90, s64, v91
	v_mad_i64_i32 v[88:89], s[12:13], v90, s67, v[88:89]
	v_lshlrev_b32_e32 v90, 3, v0
	v_ashrrev_i32_e32 v91, 31, v90
	v_lshl_add_u64 v[88:89], v[90:91], 1, v[88:89]
	global_load_dwordx4 v[220:223], v[88:89], off
	s_mov_b32 s12, 0
	v_add_u32_e32 v98, s12, v189
	v_ashrrev_i32_e32 v92, 3, v98
	v_ashrrev_i32_e32 v93, 31, v92
	v_lshlrev_b64 v[92:93], 14, v[92:93]
	v_lshl_add_u64 v[92:93], s[0:1], 0, v[92:93]
	s_lshl_b64 s[12:13], s[64:65], 1
	v_lshlrev_b32_e32 v0, 4, v98
	v_lshl_add_u64 v[92:93], v[92:93], 0, s[12:13]
	v_and_b32_e32 v0, 0x70, v0
	v_lshl_add_u64 v[92:93], v[92:93], 0, v[0:1]
	global_load_dwordx4 v[240:243], v[92:93], off
	v_add_u32_e32 v94, 0x100, v98
	v_ashrrev_i32_e32 v94, 3, v94
	v_ashrrev_i32_e32 v95, 31, v94
	v_lshlrev_b64 v[94:95], 14, v[94:95]
	v_lshl_add_u64 v[94:95], s[0:1], 0, v[94:95]
	v_lshl_add_u64 v[94:95], v[94:95], 0, s[12:13]
	v_lshl_add_u64 v[94:95], v[94:95], 0, v[0:1]
	v_add_u32_e32 v96, 0x200, v98
	v_ashrrev_i32_e32 v96, 3, v96
	v_ashrrev_i32_e32 v97, 31, v96
	v_lshlrev_b64 v[96:97], 14, v[96:97]
	v_lshl_add_u64 v[96:97], s[0:1], 0, v[96:97]
	v_lshl_add_u64 v[96:97], v[96:97], 0, s[12:13]
	v_lshl_add_u64 v[96:97], v[96:97], 0, v[0:1]
	v_add_u32_e32 v98, 0x300, v98
	v_ashrrev_i32_e32 v98, 3, v98
	v_ashrrev_i32_e32 v99, 31, v98
	v_lshlrev_b64 v[98:99], 14, v[98:99]
	v_lshl_add_u64 v[98:99], s[0:1], 0, v[98:99]
	v_lshl_add_u64 v[98:99], v[98:99], 0, s[12:13]
	v_lshl_add_u64 v[98:99], v[98:99], 0, v[0:1]
	global_load_dwordx4 v[244:247], v[94:95], off
	global_load_dwordx4 v[248:251], v[96:97], off
	global_load_dwordx4 v[182:185], v[98:99], off
